# w_o GEMM prompt epilogue (Z = alpha*x + acc): residual x loads software-pipelined 8 groups ahead with counted vmcnt instead of 16 serialized load-wait-store round trips
# baseline (speedup 1.0000x reference)
.LBB0_1445:
	v_lshl_add_u32 v158, s30, 8, v146
	v_lshl_or_b32 v156, s0, 8, v147
	v_readlane_b32 s76, v239, 17
	v_readlane_b32 s77, v239, 18
	v_readlane_b32 s78, v239, 19
	v_readlane_b32 s79, v239, 20
	v_readlane_b32 s80, v239, 21
	v_readlane_b32 s81, v239, 22
	v_readlane_b32 s82, v239, 23
	v_readlane_b32 s83, v239, 24
	v_readlane_b32 s84, v239, 25
	v_readlane_b32 s85, v239, 26
	v_readlane_b32 s86, v239, 27
	v_readlane_b32 s87, v239, 28
	v_readlane_b32 s88, v239, 29
	v_readlane_b32 s89, v239, 30
	v_readlane_b32 s90, v239, 31
	v_readlane_b32 s91, v239, 32
	v_ashrrev_i32_e32 v159, 31, v158
	v_ashrrev_i32_e32 v157, 31, v156
	v_lshlrev_b64 v[128:129], 13, v[158:159]
	v_lshlrev_b64 v[130:131], 2, v[156:157]
	v_lshl_add_u64 v[128:129], v[128:129], 0, v[130:131]
	v_lshl_add_u64 v[132:133], s[76:77], 0, v[128:129]
	v_lshl_add_u64 v[134:135], s[92:93], 0, v[128:129]
	global_load_dwordx4 v[172:175], v[132:133], off
	global_load_dwordx4 v[176:179], v[132:133], off offset:16
	global_load_dwordx4 v[180:183], v[132:133], off offset:512
	global_load_dwordx4 v[184:187], v[132:133], off offset:528
	s_mov_b32 s0, 0x20000
	s_mov_b32 s1, 0
	v_lshl_add_u64 v[162:163], v[132:133], 0, s[0:1]
	global_load_dwordx4 v[188:191], v[162:163], off
	global_load_dwordx4 v[192:195], v[162:163], off offset:16
	s_mov_b32 s0, 0x20000
	s_mov_b32 s1, 0
	v_lshl_add_u64 v[162:163], v[132:133], 0, s[0:1]
	global_load_dwordx4 v[196:199], v[162:163], off offset:512
	global_load_dwordx4 v[200:203], v[162:163], off offset:528
	s_mov_b32 s0, 0x40000
	s_mov_b32 s1, 0
	v_lshl_add_u64 v[162:163], v[132:133], 0, s[0:1]
	global_load_dwordx4 v[204:207], v[162:163], off
	global_load_dwordx4 v[208:211], v[162:163], off offset:16
	s_mov_b32 s0, 0x40000
	s_mov_b32 s1, 0
	v_lshl_add_u64 v[162:163], v[132:133], 0, s[0:1]
	global_load_dwordx4 v[212:215], v[162:163], off offset:512
	global_load_dwordx4 v[216:219], v[162:163], off offset:528
	s_mov_b32 s0, 0x60000
	s_mov_b32 s1, 0
	v_lshl_add_u64 v[162:163], v[132:133], 0, s[0:1]
	global_load_dwordx4 v[220:223], v[162:163], off
	global_load_dwordx4 v[224:227], v[162:163], off offset:16
	s_mov_b32 s0, 0x60000
	s_mov_b32 s1, 0
	v_lshl_add_u64 v[162:163], v[132:133], 0, s[0:1]
	global_load_dwordx4 v[228:231], v[162:163], off offset:512
	global_load_dwordx4 v[232:235], v[162:163], off offset:528
	s_waitcnt vmcnt(14)
	v_pk_fma_f32 v[124:125], v[172:173], s[18:19], v[124:125] op_sel_hi:[1,0,1]
	v_pk_fma_f32 v[126:127], v[174:175], s[18:19], v[126:127] op_sel_hi:[1,0,1]
	v_pk_fma_f32 v[120:121], v[176:177], s[18:19], v[120:121] op_sel_hi:[1,0,1]
	v_pk_fma_f32 v[122:123], v[178:179], s[18:19], v[122:123] op_sel_hi:[1,0,1]
	global_store_dwordx4 v[134:135], v[124:127], off
	global_store_dwordx4 v[134:135], v[120:123], off offset:16
	s_mov_b32 s0, 0x100000
	s_mov_b32 s1, 0
	v_lshl_add_u64 v[162:163], v[132:133], 0, s[0:1]
	global_load_dwordx4 v[172:175], v[162:163], off
	global_load_dwordx4 v[176:179], v[162:163], off offset:16
	s_waitcnt vmcnt(16)
	v_pk_fma_f32 v[116:117], v[180:181], s[18:19], v[116:117] op_sel_hi:[1,0,1]
	v_pk_fma_f32 v[118:119], v[182:183], s[18:19], v[118:119] op_sel_hi:[1,0,1]
	v_pk_fma_f32 v[112:113], v[184:185], s[18:19], v[112:113] op_sel_hi:[1,0,1]
	v_pk_fma_f32 v[114:115], v[186:187], s[18:19], v[114:115] op_sel_hi:[1,0,1]
	global_store_dwordx4 v[134:135], v[116:119], off offset:512
	global_store_dwordx4 v[134:135], v[112:115], off offset:528
	s_mov_b32 s0, 0x100000
	s_mov_b32 s1, 0
	v_lshl_add_u64 v[162:163], v[132:133], 0, s[0:1]
	global_load_dwordx4 v[180:183], v[162:163], off offset:512
	global_load_dwordx4 v[184:187], v[162:163], off offset:528
	s_waitcnt vmcnt(18)
	v_pk_fma_f32 v[108:109], v[188:189], s[18:19], v[108:109] op_sel_hi:[1,0,1]
	v_pk_fma_f32 v[110:111], v[190:191], s[18:19], v[110:111] op_sel_hi:[1,0,1]
	v_pk_fma_f32 v[104:105], v[192:193], s[18:19], v[104:105] op_sel_hi:[1,0,1]
	v_pk_fma_f32 v[106:107], v[194:195], s[18:19], v[106:107] op_sel_hi:[1,0,1]
	s_mov_b32 s0, 0x20000
	s_mov_b32 s1, 0
	v_lshl_add_u64 v[164:165], v[134:135], 0, s[0:1]
	global_store_dwordx4 v[164:165], v[108:111], off
	global_store_dwordx4 v[164:165], v[104:107], off offset:16
	s_mov_b32 s0, 0x120000
	s_mov_b32 s1, 0
	v_lshl_add_u64 v[162:163], v[132:133], 0, s[0:1]
	global_load_dwordx4 v[188:191], v[162:163], off
	global_load_dwordx4 v[192:195], v[162:163], off offset:16
	s_waitcnt vmcnt(20)
	v_pk_fma_f32 v[100:101], v[196:197], s[18:19], v[100:101] op_sel_hi:[1,0,1]
	v_pk_fma_f32 v[102:103], v[198:199], s[18:19], v[102:103] op_sel_hi:[1,0,1]
	v_pk_fma_f32 v[96:97], v[200:201], s[18:19], v[96:97] op_sel_hi:[1,0,1]
	v_pk_fma_f32 v[98:99], v[202:203], s[18:19], v[98:99] op_sel_hi:[1,0,1]
	s_mov_b32 s0, 0x20000
	s_mov_b32 s1, 0
	v_lshl_add_u64 v[164:165], v[134:135], 0, s[0:1]
	global_store_dwordx4 v[164:165], v[100:103], off offset:512
	global_store_dwordx4 v[164:165], v[96:99], off offset:528
	s_mov_b32 s0, 0x120000
	s_mov_b32 s1, 0
	v_lshl_add_u64 v[162:163], v[132:133], 0, s[0:1]
	global_load_dwordx4 v[196:199], v[162:163], off offset:512
	global_load_dwordx4 v[200:203], v[162:163], off offset:528
	s_waitcnt vmcnt(22)
	v_pk_fma_f32 v[92:93], v[204:205], s[18:19], v[92:93] op_sel_hi:[1,0,1]
	v_pk_fma_f32 v[94:95], v[206:207], s[18:19], v[94:95] op_sel_hi:[1,0,1]
	v_pk_fma_f32 v[88:89], v[208:209], s[18:19], v[88:89] op_sel_hi:[1,0,1]
	v_pk_fma_f32 v[90:91], v[210:211], s[18:19], v[90:91] op_sel_hi:[1,0,1]
	s_mov_b32 s0, 0x40000
	s_mov_b32 s1, 0
	v_lshl_add_u64 v[164:165], v[134:135], 0, s[0:1]
	global_store_dwordx4 v[164:165], v[92:95], off
	global_store_dwordx4 v[164:165], v[88:91], off offset:16
	s_mov_b32 s0, 0x140000
	s_mov_b32 s1, 0
	v_lshl_add_u64 v[162:163], v[132:133], 0, s[0:1]
	global_load_dwordx4 v[204:207], v[162:163], off
	global_load_dwordx4 v[208:211], v[162:163], off offset:16
	s_waitcnt vmcnt(24)
	v_pk_fma_f32 v[84:85], v[212:213], s[18:19], v[84:85] op_sel_hi:[1,0,1]
	v_pk_fma_f32 v[86:87], v[214:215], s[18:19], v[86:87] op_sel_hi:[1,0,1]
	v_pk_fma_f32 v[80:81], v[216:217], s[18:19], v[80:81] op_sel_hi:[1,0,1]
	v_pk_fma_f32 v[82:83], v[218:219], s[18:19], v[82:83] op_sel_hi:[1,0,1]
	s_mov_b32 s0, 0x40000
	s_mov_b32 s1, 0
	v_lshl_add_u64 v[164:165], v[134:135], 0, s[0:1]
	global_store_dwordx4 v[164:165], v[84:87], off offset:512
	global_store_dwordx4 v[164:165], v[80:83], off offset:528
	s_mov_b32 s0, 0x140000
	s_mov_b32 s1, 0
	v_lshl_add_u64 v[162:163], v[132:133], 0, s[0:1]
	global_load_dwordx4 v[212:215], v[162:163], off offset:512
	global_load_dwordx4 v[216:219], v[162:163], off offset:528
	s_waitcnt vmcnt(26)
	v_pk_fma_f32 v[76:77], v[220:221], s[18:19], v[76:77] op_sel_hi:[1,0,1]
	v_pk_fma_f32 v[78:79], v[222:223], s[18:19], v[78:79] op_sel_hi:[1,0,1]
	v_pk_fma_f32 v[72:73], v[224:225], s[18:19], v[72:73] op_sel_hi:[1,0,1]
	v_pk_fma_f32 v[74:75], v[226:227], s[18:19], v[74:75] op_sel_hi:[1,0,1]
	s_mov_b32 s0, 0x60000
	s_mov_b32 s1, 0
	v_lshl_add_u64 v[164:165], v[134:135], 0, s[0:1]
	global_store_dwordx4 v[164:165], v[76:79], off
	global_store_dwordx4 v[164:165], v[72:75], off offset:16
	s_mov_b32 s0, 0x160000
	s_mov_b32 s1, 0
	v_lshl_add_u64 v[162:163], v[132:133], 0, s[0:1]
	global_load_dwordx4 v[220:223], v[162:163], off
	global_load_dwordx4 v[224:227], v[162:163], off offset:16
	s_waitcnt vmcnt(28)
	v_pk_fma_f32 v[68:69], v[228:229], s[18:19], v[68:69] op_sel_hi:[1,0,1]
	v_pk_fma_f32 v[70:71], v[230:231], s[18:19], v[70:71] op_sel_hi:[1,0,1]
	v_pk_fma_f32 v[64:65], v[232:233], s[18:19], v[64:65] op_sel_hi:[1,0,1]
	v_pk_fma_f32 v[66:67], v[234:235], s[18:19], v[66:67] op_sel_hi:[1,0,1]
	s_mov_b32 s0, 0x60000
	s_mov_b32 s1, 0
	v_lshl_add_u64 v[164:165], v[134:135], 0, s[0:1]
	global_store_dwordx4 v[164:165], v[68:71], off offset:512
	global_store_dwordx4 v[164:165], v[64:67], off offset:528
	s_mov_b32 s0, 0x160000
	s_mov_b32 s1, 0
	v_lshl_add_u64 v[162:163], v[132:133], 0, s[0:1]
	global_load_dwordx4 v[228:231], v[162:163], off offset:512
	global_load_dwordx4 v[232:235], v[162:163], off offset:528
	s_waitcnt vmcnt(28)
	v_pk_fma_f32 v[60:61], v[172:173], s[18:19], v[60:61] op_sel_hi:[1,0,1]
	v_pk_fma_f32 v[62:63], v[174:175], s[18:19], v[62:63] op_sel_hi:[1,0,1]
	v_pk_fma_f32 v[56:57], v[176:177], s[18:19], v[56:57] op_sel_hi:[1,0,1]
	v_pk_fma_f32 v[58:59], v[178:179], s[18:19], v[58:59] op_sel_hi:[1,0,1]
	s_mov_b32 s0, 0x100000
	s_mov_b32 s1, 0
	v_lshl_add_u64 v[164:165], v[134:135], 0, s[0:1]
	global_store_dwordx4 v[164:165], v[60:63], off
	global_store_dwordx4 v[164:165], v[56:59], off offset:16
	s_waitcnt vmcnt(26)
	v_pk_fma_f32 v[52:53], v[180:181], s[18:19], v[52:53] op_sel_hi:[1,0,1]
	v_pk_fma_f32 v[54:55], v[182:183], s[18:19], v[54:55] op_sel_hi:[1,0,1]
	v_pk_fma_f32 v[48:49], v[184:185], s[18:19], v[48:49] op_sel_hi:[1,0,1]
	v_pk_fma_f32 v[50:51], v[186:187], s[18:19], v[50:51] op_sel_hi:[1,0,1]
	s_mov_b32 s0, 0x100000
	s_mov_b32 s1, 0
	v_lshl_add_u64 v[164:165], v[134:135], 0, s[0:1]
	global_store_dwordx4 v[164:165], v[52:55], off offset:512
	global_store_dwordx4 v[164:165], v[48:51], off offset:528
	s_waitcnt vmcnt(24)
	v_pk_fma_f32 v[44:45], v[188:189], s[18:19], v[44:45] op_sel_hi:[1,0,1]
	v_pk_fma_f32 v[46:47], v[190:191], s[18:19], v[46:47] op_sel_hi:[1,0,1]
	v_pk_fma_f32 v[40:41], v[192:193], s[18:19], v[40:41] op_sel_hi:[1,0,1]
	v_pk_fma_f32 v[42:43], v[194:195], s[18:19], v[42:43] op_sel_hi:[1,0,1]
	s_mov_b32 s0, 0x120000
	s_mov_b32 s1, 0
	v_lshl_add_u64 v[164:165], v[134:135], 0, s[0:1]
	global_store_dwordx4 v[164:165], v[44:47], off
	global_store_dwordx4 v[164:165], v[40:43], off offset:16
	s_waitcnt vmcnt(22)
	v_pk_fma_f32 v[36:37], v[196:197], s[18:19], v[36:37] op_sel_hi:[1,0,1]
	v_pk_fma_f32 v[38:39], v[198:199], s[18:19], v[38:39] op_sel_hi:[1,0,1]
	v_pk_fma_f32 v[32:33], v[200:201], s[18:19], v[32:33] op_sel_hi:[1,0,1]
	v_pk_fma_f32 v[34:35], v[202:203], s[18:19], v[34:35] op_sel_hi:[1,0,1]
	s_mov_b32 s0, 0x120000
	s_mov_b32 s1, 0
	v_lshl_add_u64 v[164:165], v[134:135], 0, s[0:1]
	global_store_dwordx4 v[164:165], v[36:39], off offset:512
	global_store_dwordx4 v[164:165], v[32:35], off offset:528
	s_waitcnt vmcnt(20)
	v_pk_fma_f32 v[28:29], v[204:205], s[18:19], v[28:29] op_sel_hi:[1,0,1]
	v_pk_fma_f32 v[30:31], v[206:207], s[18:19], v[30:31] op_sel_hi:[1,0,1]
	v_pk_fma_f32 v[24:25], v[208:209], s[18:19], v[24:25] op_sel_hi:[1,0,1]
	v_pk_fma_f32 v[26:27], v[210:211], s[18:19], v[26:27] op_sel_hi:[1,0,1]
	s_mov_b32 s0, 0x140000
	s_mov_b32 s1, 0
	v_lshl_add_u64 v[164:165], v[134:135], 0, s[0:1]
	global_store_dwordx4 v[164:165], v[28:31], off
	global_store_dwordx4 v[164:165], v[24:27], off offset:16
	s_waitcnt vmcnt(18)
	v_pk_fma_f32 v[20:21], v[212:213], s[18:19], v[20:21] op_sel_hi:[1,0,1]
	v_pk_fma_f32 v[22:23], v[214:215], s[18:19], v[22:23] op_sel_hi:[1,0,1]
	v_pk_fma_f32 v[16:17], v[216:217], s[18:19], v[16:17] op_sel_hi:[1,0,1]
	v_pk_fma_f32 v[18:19], v[218:219], s[18:19], v[18:19] op_sel_hi:[1,0,1]
	s_mov_b32 s0, 0x140000
	s_mov_b32 s1, 0
	v_lshl_add_u64 v[164:165], v[134:135], 0, s[0:1]
	global_store_dwordx4 v[164:165], v[20:23], off offset:512
	global_store_dwordx4 v[164:165], v[16:19], off offset:528
	s_waitcnt vmcnt(16)
	v_pk_fma_f32 v[12:13], v[220:221], s[18:19], v[12:13] op_sel_hi:[1,0,1]
	v_pk_fma_f32 v[14:15], v[222:223], s[18:19], v[14:15] op_sel_hi:[1,0,1]
	v_pk_fma_f32 v[8:9], v[224:225], s[18:19], v[8:9] op_sel_hi:[1,0,1]
	v_pk_fma_f32 v[10:11], v[226:227], s[18:19], v[10:11] op_sel_hi:[1,0,1]
	s_mov_b32 s0, 0x160000
	s_mov_b32 s1, 0
	v_lshl_add_u64 v[164:165], v[134:135], 0, s[0:1]
	global_store_dwordx4 v[164:165], v[12:15], off
	global_store_dwordx4 v[164:165], v[8:11], off offset:16
	s_waitcnt vmcnt(14)
	v_pk_fma_f32 v[4:5], v[228:229], s[18:19], v[4:5] op_sel_hi:[1,0,1]
	v_pk_fma_f32 v[6:7], v[230:231], s[18:19], v[6:7] op_sel_hi:[1,0,1]
	v_pk_fma_f32 v[0:1], v[232:233], s[18:19], v[0:1] op_sel_hi:[1,0,1]
	v_pk_fma_f32 v[2:3], v[234:235], s[18:19], v[2:3] op_sel_hi:[1,0,1]
	s_mov_b32 s0, 0x160000
	s_mov_b32 s1, 0
	v_lshl_add_u64 v[164:165], v[134:135], 0, s[0:1]
	global_store_dwordx4 v[164:165], v[4:7], off offset:512
	global_store_dwordx4 v[164:165], v[0:3], off offset:528
	s_and_b64 vcc, exec, s[4:5]
	s_mov_b64 s[0:1], -1
	s_cbranch_vccnz .LBB0_1425
	s_branch .LBB0_1496

.LBB0_1496:
	s_andn2_b64 vcc, exec, s[10:11]
	s_cbranch_vccnz .LBB0_1424
	s_barrier
	s_branch .LBB0_1424
.LBB0_1514:
	s_waitcnt vmcnt(0)
	s_barrier
